# P2a S3 decay-mask stage: the 16 L-path blocks made branch-free (unconditional beta reads + v_cndmask instead of exec masking); earlier changes kept
# speedup vs baseline: 1.0122x; 1.0122x over previous
; #define LAS __attribute__((address_space(3)))
; __device__ __forceinline__ void gdn_prep_phase(LAS unsigned char* lds, const GdnPrepArgs& A, int bid, int G, const unsigned char* zero_page) {
;     ...
;         for (int reg = 0; reg < 16; ++reg) {
;             const int i = 32 * rt + (reg & 3) + 8 * (reg >> 2) + 4 * hh; const float val = acc[reg];
;             const float ef = __expf(sc[i] - gfj), eb = __expf(sc[64 + i] - gbj);
;             if (which == 0) {
;                 const float lf = (i > j) ? sc[128 + i] * val * ef : 0.f, lb = (i < j) ? sc[192 + i] * val * eb : 0.f;
;                 ((LAS float*)(lds + L_LPF))[i * 64 + (j & 3) * 16 + (j >> 2)] = lf;
;                 const int i2 = 63 - i, j2 = 63 - j;
;                 ((LAS float*)(lds + L_LPB))[i2 * 64 + (j2 & 3) * 16 + (j2 >> 2)] = lb;
.LBB0_211:
	s_andn2_b64 vcc, exec, s[46:47]
	s_cbranch_vccnz .LBB0_217
	ds_read2st64_b32 v[44:45], v72 offset0:2 offset1:3
	v_readlane_b32 s46, v255, 15
	v_readlane_b32 s47, v255, 16
	s_waitcnt lgkmcnt(0)
	v_mul_f32_e32 v44, v2, v44
	v_mul_f32_e32 v45, v2, v45
	v_mul_f32_e32 v44, v35, v44
	v_mul_f32_e32 v45, v34, v45
	v_cndmask_b32_e64 v44, 0, v44, s[46:47]
	v_cndmask_b32_e64 v45, 0, v45, s[6:7]
	ds_write_b32 v192, v44
	ds_write_b32 v73, v45

; #define LAS __attribute__((address_space(3)))
; __device__ __forceinline__ void gdn_prep_phase(LAS unsigned char* lds, const GdnPrepArgs& A, int bid, int G, const unsigned char* zero_page) {
;     ...
;         for (int reg = 0; reg < 16; ++reg) {
;             const int i = 32 * rt + (reg & 3) + 8 * (reg >> 2) + 4 * hh; const float val = acc[reg];
;             const float ef = __expf(sc[i] - gfj), eb = __expf(sc[64 + i] - gbj);
;             if (which == 0) {
;                 const float lf = (i > j) ? sc[128 + i] * val * ef : 0.f, lb = (i < j) ? sc[192 + i] * val * eb : 0.f;
;                 ((LAS float*)(lds + L_LPF))[i * 64 + (j & 3) * 16 + (j >> 2)] = lf;
;                 const int i2 = 63 - i, j2 = 63 - j;
;                 ((LAS float*)(lds + L_LPB))[i2 * 64 + (j2 & 3) * 16 + (j2 >> 2)] = lb;
.LBB0_219:
	s_andn2_b64 vcc, exec, s[46:47]
	s_cbranch_vccnz .LBB0_225
	ds_read2st64_b32 v[44:45], v74 offset0:2 offset1:3
	v_readlane_b32 s46, v255, 13
	v_readlane_b32 s47, v255, 14
	v_readlane_b32 s48, v255, 17
	v_readlane_b32 s49, v255, 18
	s_waitcnt lgkmcnt(0)
	v_mul_f32_e32 v44, v3, v44
	v_mul_f32_e32 v45, v3, v45
	v_mul_f32_e32 v44, v34, v44
	v_mul_f32_e32 v45, v2, v45
	v_cndmask_b32_e64 v44, 0, v44, s[46:47]
	v_cndmask_b32_e64 v45, 0, v45, s[48:49]
	ds_write_b32 v193, v44
	ds_write_b32 v75, v45

; #define LAS __attribute__((address_space(3)))
; __device__ __forceinline__ void gdn_prep_phase(LAS unsigned char* lds, const GdnPrepArgs& A, int bid, int G, const unsigned char* zero_page) {
;     ...
;         for (int reg = 0; reg < 16; ++reg) {
;             const int i = 32 * rt + (reg & 3) + 8 * (reg >> 2) + 4 * hh; const float val = acc[reg];
;             const float ef = __expf(sc[i] - gfj), eb = __expf(sc[64 + i] - gbj);
;             if (which == 0) {
;                 const float lf = (i > j) ? sc[128 + i] * val * ef : 0.f, lb = (i < j) ? sc[192 + i] * val * eb : 0.f;
;                 ((LAS float*)(lds + L_LPF))[i * 64 + (j & 3) * 16 + (j >> 2)] = lf;
;                 const int i2 = 63 - i, j2 = 63 - j;
;                 ((LAS float*)(lds + L_LPB))[i2 * 64 + (j2 & 3) * 16 + (j2 >> 2)] = lb;
.LBB0_227:
	s_andn2_b64 vcc, exec, s[46:47]
	s_cbranch_vccnz .LBB0_233
	ds_read2st64_b32 v[44:45], v76 offset0:2 offset1:3
	v_readlane_b32 s46, v255, 21
	v_readlane_b32 s47, v255, 22
	v_readlane_b32 s48, v255, 19
	v_readlane_b32 s49, v255, 20
	s_waitcnt lgkmcnt(0)
	v_mul_f32_e32 v44, v4, v44
	v_mul_f32_e32 v45, v4, v45
	v_mul_f32_e32 v44, v3, v44
	v_mul_f32_e32 v45, v2, v45
	v_cndmask_b32_e64 v44, 0, v44, s[46:47]
	v_cndmask_b32_e64 v45, 0, v45, s[48:49]
	ds_write_b32 v194, v44
	ds_write_b32 v77, v45

; #define LAS __attribute__((address_space(3)))
; __device__ __forceinline__ void gdn_prep_phase(LAS unsigned char* lds, const GdnPrepArgs& A, int bid, int G, const unsigned char* zero_page) {
;     ...
;         for (int reg = 0; reg < 16; ++reg) {
;             const int i = 32 * rt + (reg & 3) + 8 * (reg >> 2) + 4 * hh; const float val = acc[reg];
;             const float ef = __expf(sc[i] - gfj), eb = __expf(sc[64 + i] - gbj);
;             if (which == 0) {
;                 const float lf = (i > j) ? sc[128 + i] * val * ef : 0.f, lb = (i < j) ? sc[192 + i] * val * eb : 0.f;
;                 ((LAS float*)(lds + L_LPF))[i * 64 + (j & 3) * 16 + (j >> 2)] = lf;
;                 const int i2 = 63 - i, j2 = 63 - j;
;                 ((LAS float*)(lds + L_LPB))[i2 * 64 + (j2 & 3) * 16 + (j2 >> 2)] = lb;
.LBB0_235:
	s_andn2_b64 vcc, exec, s[46:47]
	s_cbranch_vccnz .LBB0_241
	ds_read2st64_b32 v[44:45], v78 offset0:2 offset1:3
	v_readlane_b32 s46, v255, 25
	v_readlane_b32 s47, v255, 26
	v_readlane_b32 s48, v255, 23
	v_readlane_b32 s49, v255, 24
	s_waitcnt lgkmcnt(0)
	v_mul_f32_e32 v44, v5, v44
	v_mul_f32_e32 v45, v5, v45
	v_mul_f32_e32 v44, v3, v44
	v_mul_f32_e32 v45, v2, v45
	v_cndmask_b32_e64 v44, 0, v44, s[46:47]
	v_cndmask_b32_e64 v45, 0, v45, s[48:49]
	ds_write_b32 v195, v44
	ds_write_b32 v79, v45

; #define LAS __attribute__((address_space(3)))
; __device__ __forceinline__ void gdn_prep_phase(LAS unsigned char* lds, const GdnPrepArgs& A, int bid, int G, const unsigned char* zero_page) {
;     ...
;         for (int reg = 0; reg < 16; ++reg) {
;             const int i = 32 * rt + (reg & 3) + 8 * (reg >> 2) + 4 * hh; const float val = acc[reg];
;             const float ef = __expf(sc[i] - gfj), eb = __expf(sc[64 + i] - gbj);
;             if (which == 0) {
;                 const float lf = (i > j) ? sc[128 + i] * val * ef : 0.f, lb = (i < j) ? sc[192 + i] * val * eb : 0.f;
;                 ((LAS float*)(lds + L_LPF))[i * 64 + (j & 3) * 16 + (j >> 2)] = lf;
;                 const int i2 = 63 - i, j2 = 63 - j;
;                 ((LAS float*)(lds + L_LPB))[i2 * 64 + (j2 & 3) * 16 + (j2 >> 2)] = lb;
.LBB0_243:
	s_andn2_b64 vcc, exec, s[46:47]
	s_cbranch_vccnz .LBB0_249
	ds_read2st64_b32 v[44:45], v80 offset0:2 offset1:3
	v_readlane_b32 s46, v255, 29
	v_readlane_b32 s47, v255, 30
	v_readlane_b32 s48, v255, 27
	v_readlane_b32 s49, v255, 28
	s_waitcnt lgkmcnt(0)
	v_mul_f32_e32 v44, v6, v44
	v_mul_f32_e32 v45, v6, v45
	v_mul_f32_e32 v44, v3, v44
	v_mul_f32_e32 v45, v2, v45
	v_cndmask_b32_e64 v44, 0, v44, s[46:47]
	v_cndmask_b32_e64 v45, 0, v45, s[48:49]
	ds_write_b32 v196, v44
	ds_write_b32 v81, v45

; #define LAS __attribute__((address_space(3)))
; __device__ __forceinline__ void gdn_prep_phase(LAS unsigned char* lds, const GdnPrepArgs& A, int bid, int G, const unsigned char* zero_page) {
;     ...
;         for (int reg = 0; reg < 16; ++reg) {
;             const int i = 32 * rt + (reg & 3) + 8 * (reg >> 2) + 4 * hh; const float val = acc[reg];
;             const float ef = __expf(sc[i] - gfj), eb = __expf(sc[64 + i] - gbj);
;             if (which == 0) {
;                 const float lf = (i > j) ? sc[128 + i] * val * ef : 0.f, lb = (i < j) ? sc[192 + i] * val * eb : 0.f;
;                 ((LAS float*)(lds + L_LPF))[i * 64 + (j & 3) * 16 + (j >> 2)] = lf;
;                 const int i2 = 63 - i, j2 = 63 - j;
;                 ((LAS float*)(lds + L_LPB))[i2 * 64 + (j2 & 3) * 16 + (j2 >> 2)] = lb;
.LBB0_251:
	s_andn2_b64 vcc, exec, s[46:47]
	s_cbranch_vccnz .LBB0_257
	ds_read2st64_b32 v[44:45], v82 offset0:2 offset1:3
	v_readlane_b32 s46, v255, 33
	v_readlane_b32 s47, v255, 34
	v_readlane_b32 s48, v255, 31
	v_readlane_b32 s49, v255, 32
	s_waitcnt lgkmcnt(0)
	v_mul_f32_e32 v44, v7, v44
	v_mul_f32_e32 v45, v7, v45
	v_mul_f32_e32 v44, v3, v44
	v_mul_f32_e32 v45, v2, v45
	v_cndmask_b32_e64 v44, 0, v44, s[46:47]
	v_cndmask_b32_e64 v45, 0, v45, s[48:49]
	ds_write_b32 v197, v44
	ds_write_b32 v83, v45

; #define LAS __attribute__((address_space(3)))
; __device__ __forceinline__ void gdn_prep_phase(LAS unsigned char* lds, const GdnPrepArgs& A, int bid, int G, const unsigned char* zero_page) {
;     ...
;         for (int reg = 0; reg < 16; ++reg) {
;             const int i = 32 * rt + (reg & 3) + 8 * (reg >> 2) + 4 * hh; const float val = acc[reg];
;             const float ef = __expf(sc[i] - gfj), eb = __expf(sc[64 + i] - gbj);
;             if (which == 0) {
;                 const float lf = (i > j) ? sc[128 + i] * val * ef : 0.f, lb = (i < j) ? sc[192 + i] * val * eb : 0.f;
;                 ((LAS float*)(lds + L_LPF))[i * 64 + (j & 3) * 16 + (j >> 2)] = lf;
;                 const int i2 = 63 - i, j2 = 63 - j;
;                 ((LAS float*)(lds + L_LPB))[i2 * 64 + (j2 & 3) * 16 + (j2 >> 2)] = lb;
.LBB0_259:
	s_andn2_b64 vcc, exec, s[46:47]
	s_cbranch_vccnz .LBB0_265
	ds_read2st64_b32 v[44:45], v84 offset0:2 offset1:3
	v_readlane_b32 s46, v255, 37
	v_readlane_b32 s47, v255, 38
	v_readlane_b32 s48, v255, 35
	v_readlane_b32 s49, v255, 36
	s_waitcnt lgkmcnt(0)
	v_mul_f32_e32 v44, v8, v44
	v_mul_f32_e32 v45, v8, v45
	v_mul_f32_e32 v44, v3, v44
	v_mul_f32_e32 v45, v2, v45
	v_cndmask_b32_e64 v44, 0, v44, s[46:47]
	v_cndmask_b32_e64 v45, 0, v45, s[48:49]
	ds_write_b32 v198, v44
	ds_write_b32 v85, v45

; #define LAS __attribute__((address_space(3)))
; __device__ __forceinline__ void gdn_prep_phase(LAS unsigned char* lds, const GdnPrepArgs& A, int bid, int G, const unsigned char* zero_page) {
;     ...
;         for (int reg = 0; reg < 16; ++reg) {
;             const int i = 32 * rt + (reg & 3) + 8 * (reg >> 2) + 4 * hh; const float val = acc[reg];
;             const float ef = __expf(sc[i] - gfj), eb = __expf(sc[64 + i] - gbj);
;             if (which == 0) {
;                 const float lf = (i > j) ? sc[128 + i] * val * ef : 0.f, lb = (i < j) ? sc[192 + i] * val * eb : 0.f;
;                 ((LAS float*)(lds + L_LPF))[i * 64 + (j & 3) * 16 + (j >> 2)] = lf;
;                 const int i2 = 63 - i, j2 = 63 - j;
;                 ((LAS float*)(lds + L_LPB))[i2 * 64 + (j2 & 3) * 16 + (j2 >> 2)] = lb;
.LBB0_267:
	s_andn2_b64 vcc, exec, s[46:47]
	s_cbranch_vccnz .LBB0_273
	ds_read2st64_b32 v[44:45], v86 offset0:2 offset1:3
	v_readlane_b32 s46, v255, 41
	v_readlane_b32 s47, v255, 42
	v_readlane_b32 s48, v255, 39
	v_readlane_b32 s49, v255, 40
	s_waitcnt lgkmcnt(0)
	v_mul_f32_e32 v44, v9, v44
	v_mul_f32_e32 v45, v9, v45
	v_mul_f32_e32 v44, v3, v44
	v_mul_f32_e32 v45, v2, v45
	v_cndmask_b32_e64 v44, 0, v44, s[46:47]
	v_cndmask_b32_e64 v45, 0, v45, s[48:49]
	ds_write_b32 v199, v44
	ds_write_b32 v87, v45

; #define LAS __attribute__((address_space(3)))
; __device__ __forceinline__ void gdn_prep_phase(LAS unsigned char* lds, const GdnPrepArgs& A, int bid, int G, const unsigned char* zero_page) {
;     ...
;         for (int reg = 0; reg < 16; ++reg) {
;             const int i = 32 * rt + (reg & 3) + 8 * (reg >> 2) + 4 * hh; const float val = acc[reg];
;             const float ef = __expf(sc[i] - gfj), eb = __expf(sc[64 + i] - gbj);
;             if (which == 0) {
;                 const float lf = (i > j) ? sc[128 + i] * val * ef : 0.f, lb = (i < j) ? sc[192 + i] * val * eb : 0.f;
;                 ((LAS float*)(lds + L_LPF))[i * 64 + (j & 3) * 16 + (j >> 2)] = lf;
;                 const int i2 = 63 - i, j2 = 63 - j;
;                 ((LAS float*)(lds + L_LPB))[i2 * 64 + (j2 & 3) * 16 + (j2 >> 2)] = lb;
.LBB0_275:
	s_andn2_b64 vcc, exec, s[46:47]
	s_cbranch_vccnz .LBB0_281
	ds_read2st64_b32 v[44:45], v88 offset0:2 offset1:3
	v_readlane_b32 s46, v255, 45
	v_readlane_b32 s47, v255, 46
	v_readlane_b32 s48, v255, 43
	v_readlane_b32 s49, v255, 44
	s_waitcnt lgkmcnt(0)
	v_mul_f32_e32 v44, v10, v44
	v_mul_f32_e32 v45, v10, v45
	v_mul_f32_e32 v44, v3, v44
	v_mul_f32_e32 v45, v2, v45
	v_cndmask_b32_e64 v44, 0, v44, s[46:47]
	v_cndmask_b32_e64 v45, 0, v45, s[48:49]
	ds_write_b32 v200, v44
	ds_write_b32 v89, v45

; #define LAS __attribute__((address_space(3)))
; __device__ __forceinline__ void gdn_prep_phase(LAS unsigned char* lds, const GdnPrepArgs& A, int bid, int G, const unsigned char* zero_page) {
;     ...
;         for (int reg = 0; reg < 16; ++reg) {
;             const int i = 32 * rt + (reg & 3) + 8 * (reg >> 2) + 4 * hh; const float val = acc[reg];
;             const float ef = __expf(sc[i] - gfj), eb = __expf(sc[64 + i] - gbj);
;             if (which == 0) {
;                 const float lf = (i > j) ? sc[128 + i] * val * ef : 0.f, lb = (i < j) ? sc[192 + i] * val * eb : 0.f;
;                 ((LAS float*)(lds + L_LPF))[i * 64 + (j & 3) * 16 + (j >> 2)] = lf;
;                 const int i2 = 63 - i, j2 = 63 - j;
;                 ((LAS float*)(lds + L_LPB))[i2 * 64 + (j2 & 3) * 16 + (j2 >> 2)] = lb;
.LBB0_283:
	s_andn2_b64 vcc, exec, s[46:47]
	s_cbranch_vccnz .LBB0_289
	ds_read2st64_b32 v[44:45], v90 offset0:2 offset1:3
	s_waitcnt lgkmcnt(0)
	v_mul_f32_e32 v44, v11, v44
	v_mul_f32_e32 v45, v11, v45
	v_mul_f32_e32 v44, v3, v44
	v_mul_f32_e32 v45, v2, v45
	v_cndmask_b32_e64 v44, 0, v44, s[76:77]
	v_cndmask_b32_e64 v45, 0, v45, s[74:75]
	ds_write_b32 v201, v44
	ds_write_b32 v91, v45

; #define LAS __attribute__((address_space(3)))
; __device__ __forceinline__ void gdn_prep_phase(LAS unsigned char* lds, const GdnPrepArgs& A, int bid, int G, const unsigned char* zero_page) {
;     ...
;         for (int reg = 0; reg < 16; ++reg) {
;             const int i = 32 * rt + (reg & 3) + 8 * (reg >> 2) + 4 * hh; const float val = acc[reg];
;             const float ef = __expf(sc[i] - gfj), eb = __expf(sc[64 + i] - gbj);
;             if (which == 0) {
;                 const float lf = (i > j) ? sc[128 + i] * val * ef : 0.f, lb = (i < j) ? sc[192 + i] * val * eb : 0.f;
;                 ((LAS float*)(lds + L_LPF))[i * 64 + (j & 3) * 16 + (j >> 2)] = lf;
;                 const int i2 = 63 - i, j2 = 63 - j;
;                 ((LAS float*)(lds + L_LPB))[i2 * 64 + (j2 & 3) * 16 + (j2 >> 2)] = lb;
.LBB0_291:
	s_andn2_b64 vcc, exec, s[46:47]
	s_cbranch_vccnz .LBB0_297
	ds_read2st64_b32 v[44:45], v92 offset0:2 offset1:3
	s_waitcnt lgkmcnt(0)
	v_mul_f32_e32 v44, v12, v44
	v_mul_f32_e32 v45, v12, v45
	v_mul_f32_e32 v44, v3, v44
	v_mul_f32_e32 v45, v2, v45
	v_cndmask_b32_e64 v44, 0, v44, s[60:61]
	v_cndmask_b32_e64 v45, 0, v45, s[58:59]
	ds_write_b32 v202, v44
	ds_write_b32 v93, v45

; #define LAS __attribute__((address_space(3)))
; __device__ __forceinline__ void gdn_prep_phase(LAS unsigned char* lds, const GdnPrepArgs& A, int bid, int G, const unsigned char* zero_page) {
;     ...
;         for (int reg = 0; reg < 16; ++reg) {
;             const int i = 32 * rt + (reg & 3) + 8 * (reg >> 2) + 4 * hh; const float val = acc[reg];
;             const float ef = __expf(sc[i] - gfj), eb = __expf(sc[64 + i] - gbj);
;             if (which == 0) {
;                 const float lf = (i > j) ? sc[128 + i] * val * ef : 0.f, lb = (i < j) ? sc[192 + i] * val * eb : 0.f;
;                 ((LAS float*)(lds + L_LPF))[i * 64 + (j & 3) * 16 + (j >> 2)] = lf;
;                 const int i2 = 63 - i, j2 = 63 - j;
;                 ((LAS float*)(lds + L_LPB))[i2 * 64 + (j2 & 3) * 16 + (j2 >> 2)] = lb;
.LBB0_299:
	s_andn2_b64 vcc, exec, s[46:47]
	s_cbranch_vccnz .LBB0_305
	ds_read2st64_b32 v[44:45], v94 offset0:2 offset1:3
	s_waitcnt lgkmcnt(0)
	v_mul_f32_e32 v44, v13, v44
	v_mul_f32_e32 v45, v13, v45
	v_mul_f32_e32 v44, v3, v44
	v_mul_f32_e32 v45, v2, v45
	v_cndmask_b32_e64 v44, 0, v44, s[64:65]
	v_cndmask_b32_e64 v45, 0, v45, s[62:63]
	ds_write_b32 v203, v44
	ds_write_b32 v95, v45

; #define LAS __attribute__((address_space(3)))
; __device__ __forceinline__ void gdn_prep_phase(LAS unsigned char* lds, const GdnPrepArgs& A, int bid, int G, const unsigned char* zero_page) {
;     ...
;         for (int reg = 0; reg < 16; ++reg) {
;             const int i = 32 * rt + (reg & 3) + 8 * (reg >> 2) + 4 * hh; const float val = acc[reg];
;             const float ef = __expf(sc[i] - gfj), eb = __expf(sc[64 + i] - gbj);
;             if (which == 0) {
;                 const float lf = (i > j) ? sc[128 + i] * val * ef : 0.f, lb = (i < j) ? sc[192 + i] * val * eb : 0.f;
;                 ((LAS float*)(lds + L_LPF))[i * 64 + (j & 3) * 16 + (j >> 2)] = lf;
;                 const int i2 = 63 - i, j2 = 63 - j;
;                 ((LAS float*)(lds + L_LPB))[i2 * 64 + (j2 & 3) * 16 + (j2 >> 2)] = lb;
.LBB0_307:
	s_andn2_b64 vcc, exec, s[46:47]
	s_cbranch_vccnz .LBB0_313
	ds_read2st64_b32 v[44:45], v96 offset0:2 offset1:3
	s_waitcnt lgkmcnt(0)
	v_mul_f32_e32 v44, v14, v44
	v_mul_f32_e32 v45, v14, v45
	v_mul_f32_e32 v44, v3, v44
	v_mul_f32_e32 v45, v2, v45
	v_cndmask_b32_e64 v44, 0, v44, s[78:79]
	v_cndmask_b32_e64 v45, 0, v45, s[84:85]
	ds_write_b32 v204, v44
	ds_write_b32 v97, v45

; #define LAS __attribute__((address_space(3)))
; __device__ __forceinline__ void gdn_prep_phase(LAS unsigned char* lds, const GdnPrepArgs& A, int bid, int G, const unsigned char* zero_page) {
;     ...
;         for (int reg = 0; reg < 16; ++reg) {
;             const int i = 32 * rt + (reg & 3) + 8 * (reg >> 2) + 4 * hh; const float val = acc[reg];
;             const float ef = __expf(sc[i] - gfj), eb = __expf(sc[64 + i] - gbj);
;             if (which == 0) {
;                 const float lf = (i > j) ? sc[128 + i] * val * ef : 0.f, lb = (i < j) ? sc[192 + i] * val * eb : 0.f;
;                 ((LAS float*)(lds + L_LPF))[i * 64 + (j & 3) * 16 + (j >> 2)] = lf;
;                 const int i2 = 63 - i, j2 = 63 - j;
;                 ((LAS float*)(lds + L_LPB))[i2 * 64 + (j2 & 3) * 16 + (j2 >> 2)] = lb;
.LBB0_315:
	s_andn2_b64 vcc, exec, s[46:47]
	s_cbranch_vccnz .LBB0_321
	ds_read2st64_b32 v[44:45], v98 offset0:2 offset1:3
	s_waitcnt lgkmcnt(0)
	v_mul_f32_e32 v44, v15, v44
	v_mul_f32_e32 v45, v15, v45
	v_mul_f32_e32 v44, v3, v44
	v_mul_f32_e32 v45, v2, v45
	v_cndmask_b32_e64 v44, 0, v44, s[26:27]
	v_cndmask_b32_e64 v45, 0, v45, s[80:81]
	ds_write_b32 v205, v44
	ds_write_b32 v99, v45

; #define LAS __attribute__((address_space(3)))
; __device__ __forceinline__ void gdn_prep_phase(LAS unsigned char* lds, const GdnPrepArgs& A, int bid, int G, const unsigned char* zero_page) {
;     ...
;         for (int reg = 0; reg < 16; ++reg) {
;             const int i = 32 * rt + (reg & 3) + 8 * (reg >> 2) + 4 * hh; const float val = acc[reg];
;             const float ef = __expf(sc[i] - gfj), eb = __expf(sc[64 + i] - gbj);
;             if (which == 0) {
;                 const float lf = (i > j) ? sc[128 + i] * val * ef : 0.f, lb = (i < j) ? sc[192 + i] * val * eb : 0.f;
;                 ((LAS float*)(lds + L_LPF))[i * 64 + (j & 3) * 16 + (j >> 2)] = lf;
;                 const int i2 = 63 - i, j2 = 63 - j;
;                 ((LAS float*)(lds + L_LPB))[i2 * 64 + (j2 & 3) * 16 + (j2 >> 2)] = lb;
.LBB0_323:
	s_andn2_b64 vcc, exec, s[46:47]
	s_cbranch_vccnz .LBB0_329
	ds_read2st64_b32 v[44:45], v100 offset0:2 offset1:3
	s_waitcnt lgkmcnt(0)
	v_mul_f32_e32 v44, v16, v44
	v_mul_f32_e32 v45, v16, v45
	v_mul_f32_e32 v44, v3, v44
	v_mul_f32_e32 v45, v2, v45
	v_cndmask_b32_e64 v44, 0, v44, s[30:31]
	v_cndmask_b32_e64 v45, 0, v45, s[28:29]
	ds_write_b32 v206, v44
	ds_write_b32 v101, v45

; #define LAS __attribute__((address_space(3)))
; __device__ __forceinline__ void gdn_prep_phase(LAS unsigned char* lds, const GdnPrepArgs& A, int bid, int G, const unsigned char* zero_page) {
;     ...
;         for (int reg = 0; reg < 16; ++reg) {
;             const int i = 32 * rt + (reg & 3) + 8 * (reg >> 2) + 4 * hh; const float val = acc[reg];
;             const float ef = __expf(sc[i] - gfj), eb = __expf(sc[64 + i] - gbj);
;             if (which == 0) {
;                 const float lf = (i > j) ? sc[128 + i] * val * ef : 0.f, lb = (i < j) ? sc[192 + i] * val * eb : 0.f;
;                 ((LAS float*)(lds + L_LPF))[i * 64 + (j & 3) * 16 + (j >> 2)] = lf;
;                 const int i2 = 63 - i, j2 = 63 - j;
;                 ((LAS float*)(lds + L_LPB))[i2 * 64 + (j2 & 3) * 16 + (j2 >> 2)] = lb;
.LBB0_331:
	s_andn2_b64 vcc, exec, s[46:47]
	s_cbranch_vccnz .LBB0_337
	ds_read2st64_b32 v[44:45], v102 offset0:2 offset1:3
	s_waitcnt lgkmcnt(0)
	v_mul_f32_e32 v44, v17, v44
	v_mul_f32_e32 v45, v17, v45
	v_mul_f32_e32 v44, v3, v44
	v_mul_f32_e32 v45, v2, v45
	v_cndmask_b32_e64 v44, 0, v44, s[36:37]
	v_cndmask_b32_e64 v45, 0, v45, s[24:25]
	ds_write_b32 v207, v44
	ds_write_b32 v103, v45
